# v91 + skinny4: skinny_sample K-loops as a four-stage software pipeline (loads of k-step k+4 issued behind the MFMAs of k-step k, vmcnt(12))
# speedup vs baseline: 1.0029x; 1.0029x over previous
.LBB0_526:
	s_add_i32 s100, s24, 0x0
	s_ashr_i32 s101, s100, 31
	s_lshl_b64 s[100:101], s[100:101], 1
	v_lshl_add_u64 v[48:49], v[18:19], 0, s[100:101]
	v_lshl_add_u64 v[52:53], v[22:23], 0, s[100:101]
	v_lshl_add_u64 v[56:57], v[20:21], 0, s[100:101]
	v_lshl_add_u64 v[60:61], v[24:25], 0, s[100:101]
	global_load_dwordx4 v[48:51], v[48:49], off
	global_load_dwordx4 v[52:55], v[52:53], off
	global_load_dwordx4 v[56:59], v[56:57], off
	global_load_dwordx4 v[60:63], v[60:61], off
	s_cmp_gt_i32 s21, 47
	s_cbranch_scc1 .Lmy_sq0_tail3
	s_add_i32 s100, s24, 0x100
	s_ashr_i32 s101, s100, 31
	s_lshl_b64 s[100:101], s[100:101], 1
	v_lshl_add_u64 v[64:65], v[18:19], 0, s[100:101]
	v_lshl_add_u64 v[68:69], v[22:23], 0, s[100:101]
	v_lshl_add_u64 v[72:73], v[20:21], 0, s[100:101]
	v_lshl_add_u64 v[76:77], v[24:25], 0, s[100:101]
	global_load_dwordx4 v[64:67], v[64:65], off
	global_load_dwordx4 v[68:71], v[68:69], off
	global_load_dwordx4 v[72:75], v[72:73], off
	global_load_dwordx4 v[76:79], v[76:77], off
	s_cmp_gt_i32 s21, 39
	s_cbranch_scc1 .Lmy_sq0_tail3
	s_add_i32 s100, s24, 0x200
	s_ashr_i32 s101, s100, 31
	s_lshl_b64 s[100:101], s[100:101], 1
	v_lshl_add_u64 v[80:81], v[18:19], 0, s[100:101]
	v_lshl_add_u64 v[84:85], v[22:23], 0, s[100:101]
	v_lshl_add_u64 v[88:89], v[20:21], 0, s[100:101]
	v_lshl_add_u64 v[92:93], v[24:25], 0, s[100:101]
	global_load_dwordx4 v[80:83], v[80:81], off
	global_load_dwordx4 v[84:87], v[84:85], off
	global_load_dwordx4 v[88:91], v[88:89], off
	global_load_dwordx4 v[92:95], v[92:93], off
	s_cmp_gt_i32 s21, 31
	s_cbranch_scc1 .Lmy_sq0_tail3
	s_add_i32 s100, s24, 0x300
	s_ashr_i32 s101, s100, 31
	s_lshl_b64 s[100:101], s[100:101], 1
	v_lshl_add_u64 v[96:97], v[18:19], 0, s[100:101]
	v_lshl_add_u64 v[100:101], v[22:23], 0, s[100:101]
	v_lshl_add_u64 v[104:105], v[20:21], 0, s[100:101]
	v_lshl_add_u64 v[108:109], v[24:25], 0, s[100:101]
	global_load_dwordx4 v[96:99], v[96:97], off
	global_load_dwordx4 v[100:103], v[100:101], off
	global_load_dwordx4 v[104:107], v[104:105], off
	global_load_dwordx4 v[108:111], v[108:109], off
.Lmy_sq0_loop:
	s_waitcnt vmcnt(12)
	v_mfma_f32_16x16x32_bf16 v[14:17], v[48:51], v[56:59], v[14:17]
	v_mfma_f32_16x16x32_bf16 v[10:13], v[52:55], v[56:59], v[10:13]
	v_mfma_f32_16x16x32_bf16 v[6:9], v[48:51], v[60:63], v[6:9]
	v_mfma_f32_16x16x32_bf16 v[2:5], v[52:55], v[60:63], v[2:5]
	s_add_i32 s21, s21, 8
	s_addk_i32 s24, 0x100
	s_cmp_gt_i32 s21, 55
	s_cbranch_scc1 .Lmy_sq0_done
	s_cmp_gt_i32 s21, 31
	s_cbranch_scc1 .Lmy_sq0_tail0
	s_add_i32 s100, s24, 0x300
	s_ashr_i32 s101, s100, 31
	s_lshl_b64 s[100:101], s[100:101], 1
	v_lshl_add_u64 v[48:49], v[18:19], 0, s[100:101]
	v_lshl_add_u64 v[52:53], v[22:23], 0, s[100:101]
	v_lshl_add_u64 v[56:57], v[20:21], 0, s[100:101]
	v_lshl_add_u64 v[60:61], v[24:25], 0, s[100:101]
	global_load_dwordx4 v[48:51], v[48:49], off
	global_load_dwordx4 v[52:55], v[52:53], off
	global_load_dwordx4 v[56:59], v[56:57], off
	global_load_dwordx4 v[60:63], v[60:61], off
	s_waitcnt vmcnt(12)
	v_mfma_f32_16x16x32_bf16 v[14:17], v[64:67], v[72:75], v[14:17]
	v_mfma_f32_16x16x32_bf16 v[10:13], v[68:71], v[72:75], v[10:13]
	v_mfma_f32_16x16x32_bf16 v[6:9], v[64:67], v[76:79], v[6:9]
	v_mfma_f32_16x16x32_bf16 v[2:5], v[68:71], v[76:79], v[2:5]
	s_add_i32 s21, s21, 8
	s_addk_i32 s24, 0x100
	s_cmp_gt_i32 s21, 55
	s_cbranch_scc1 .Lmy_sq0_done
	s_cmp_gt_i32 s21, 31
	s_cbranch_scc1 .Lmy_sq0_tail1
	s_add_i32 s100, s24, 0x300
	s_ashr_i32 s101, s100, 31
	s_lshl_b64 s[100:101], s[100:101], 1
	v_lshl_add_u64 v[64:65], v[18:19], 0, s[100:101]
	v_lshl_add_u64 v[68:69], v[22:23], 0, s[100:101]
	v_lshl_add_u64 v[72:73], v[20:21], 0, s[100:101]
	v_lshl_add_u64 v[76:77], v[24:25], 0, s[100:101]
	global_load_dwordx4 v[64:67], v[64:65], off
	global_load_dwordx4 v[68:71], v[68:69], off
	global_load_dwordx4 v[72:75], v[72:73], off
	global_load_dwordx4 v[76:79], v[76:77], off
	s_waitcnt vmcnt(12)
	v_mfma_f32_16x16x32_bf16 v[14:17], v[80:83], v[88:91], v[14:17]
	v_mfma_f32_16x16x32_bf16 v[10:13], v[84:87], v[88:91], v[10:13]
	v_mfma_f32_16x16x32_bf16 v[6:9], v[80:83], v[92:95], v[6:9]
	v_mfma_f32_16x16x32_bf16 v[2:5], v[84:87], v[92:95], v[2:5]
	s_add_i32 s21, s21, 8
	s_addk_i32 s24, 0x100
	s_cmp_gt_i32 s21, 55
	s_cbranch_scc1 .Lmy_sq0_done
	s_cmp_gt_i32 s21, 31
	s_cbranch_scc1 .Lmy_sq0_tail2
	s_add_i32 s100, s24, 0x300
	s_ashr_i32 s101, s100, 31
	s_lshl_b64 s[100:101], s[100:101], 1
	v_lshl_add_u64 v[80:81], v[18:19], 0, s[100:101]
	v_lshl_add_u64 v[84:85], v[22:23], 0, s[100:101]
	v_lshl_add_u64 v[88:89], v[20:21], 0, s[100:101]
	v_lshl_add_u64 v[92:93], v[24:25], 0, s[100:101]
	global_load_dwordx4 v[80:83], v[80:81], off
	global_load_dwordx4 v[84:87], v[84:85], off
	global_load_dwordx4 v[88:91], v[88:89], off
	global_load_dwordx4 v[92:95], v[92:93], off
	s_waitcnt vmcnt(12)
	v_mfma_f32_16x16x32_bf16 v[14:17], v[96:99], v[104:107], v[14:17]
	v_mfma_f32_16x16x32_bf16 v[10:13], v[100:103], v[104:107], v[10:13]
	v_mfma_f32_16x16x32_bf16 v[6:9], v[96:99], v[108:111], v[6:9]
	v_mfma_f32_16x16x32_bf16 v[2:5], v[100:103], v[108:111], v[2:5]
	s_add_i32 s21, s21, 8
	s_addk_i32 s24, 0x100
	s_cmp_gt_i32 s21, 55
	s_cbranch_scc1 .Lmy_sq0_done
	s_cmp_gt_i32 s21, 31
	s_cbranch_scc1 .Lmy_sq0_tail3
	s_add_i32 s100, s24, 0x300
	s_ashr_i32 s101, s100, 31
	s_lshl_b64 s[100:101], s[100:101], 1
	v_lshl_add_u64 v[96:97], v[18:19], 0, s[100:101]
	v_lshl_add_u64 v[100:101], v[22:23], 0, s[100:101]
	v_lshl_add_u64 v[104:105], v[20:21], 0, s[100:101]
	v_lshl_add_u64 v[108:109], v[24:25], 0, s[100:101]
	global_load_dwordx4 v[96:99], v[96:97], off
	global_load_dwordx4 v[100:103], v[100:101], off
	global_load_dwordx4 v[104:107], v[104:105], off
	global_load_dwordx4 v[108:111], v[108:109], off
	s_branch .Lmy_sq0_loop
.Lmy_sq0_tail0:
	s_waitcnt vmcnt(0)
	v_mfma_f32_16x16x32_bf16 v[14:17], v[64:67], v[72:75], v[14:17]
	v_mfma_f32_16x16x32_bf16 v[10:13], v[68:71], v[72:75], v[10:13]
	v_mfma_f32_16x16x32_bf16 v[6:9], v[64:67], v[76:79], v[6:9]
	v_mfma_f32_16x16x32_bf16 v[2:5], v[68:71], v[76:79], v[2:5]
	s_add_i32 s21, s21, 8
	s_addk_i32 s24, 0x100
	s_cmp_gt_i32 s21, 55
	s_cbranch_scc1 .Lmy_sq0_done
	v_mfma_f32_16x16x32_bf16 v[14:17], v[80:83], v[88:91], v[14:17]
	v_mfma_f32_16x16x32_bf16 v[10:13], v[84:87], v[88:91], v[10:13]
	v_mfma_f32_16x16x32_bf16 v[6:9], v[80:83], v[92:95], v[6:9]
	v_mfma_f32_16x16x32_bf16 v[2:5], v[84:87], v[92:95], v[2:5]
	s_add_i32 s21, s21, 8
	s_addk_i32 s24, 0x100
	s_cmp_gt_i32 s21, 55
	s_cbranch_scc1 .Lmy_sq0_done
	v_mfma_f32_16x16x32_bf16 v[14:17], v[96:99], v[104:107], v[14:17]
	v_mfma_f32_16x16x32_bf16 v[10:13], v[100:103], v[104:107], v[10:13]
	v_mfma_f32_16x16x32_bf16 v[6:9], v[96:99], v[108:111], v[6:9]
	v_mfma_f32_16x16x32_bf16 v[2:5], v[100:103], v[108:111], v[2:5]
	s_add_i32 s21, s21, 8
	s_addk_i32 s24, 0x100
	s_cmp_gt_i32 s21, 55
	s_cbranch_scc1 .Lmy_sq0_done
	s_branch .Lmy_sq0_done
.Lmy_sq0_tail1:
	s_waitcnt vmcnt(0)
	v_mfma_f32_16x16x32_bf16 v[14:17], v[80:83], v[88:91], v[14:17]
	v_mfma_f32_16x16x32_bf16 v[10:13], v[84:87], v[88:91], v[10:13]
	v_mfma_f32_16x16x32_bf16 v[6:9], v[80:83], v[92:95], v[6:9]
	v_mfma_f32_16x16x32_bf16 v[2:5], v[84:87], v[92:95], v[2:5]
	s_add_i32 s21, s21, 8
	s_addk_i32 s24, 0x100
	s_cmp_gt_i32 s21, 55
	s_cbranch_scc1 .Lmy_sq0_done
	v_mfma_f32_16x16x32_bf16 v[14:17], v[96:99], v[104:107], v[14:17]
	v_mfma_f32_16x16x32_bf16 v[10:13], v[100:103], v[104:107], v[10:13]
	v_mfma_f32_16x16x32_bf16 v[6:9], v[96:99], v[108:111], v[6:9]
	v_mfma_f32_16x16x32_bf16 v[2:5], v[100:103], v[108:111], v[2:5]
	s_add_i32 s21, s21, 8
	s_addk_i32 s24, 0x100
	s_cmp_gt_i32 s21, 55
	s_cbranch_scc1 .Lmy_sq0_done
	v_mfma_f32_16x16x32_bf16 v[14:17], v[48:51], v[56:59], v[14:17]
	v_mfma_f32_16x16x32_bf16 v[10:13], v[52:55], v[56:59], v[10:13]
	v_mfma_f32_16x16x32_bf16 v[6:9], v[48:51], v[60:63], v[6:9]
	v_mfma_f32_16x16x32_bf16 v[2:5], v[52:55], v[60:63], v[2:5]
	s_add_i32 s21, s21, 8
	s_addk_i32 s24, 0x100
	s_cmp_gt_i32 s21, 55
	s_cbranch_scc1 .Lmy_sq0_done
	s_branch .Lmy_sq0_done
.Lmy_sq0_tail2:
	s_waitcnt vmcnt(0)
	v_mfma_f32_16x16x32_bf16 v[14:17], v[96:99], v[104:107], v[14:17]
	v_mfma_f32_16x16x32_bf16 v[10:13], v[100:103], v[104:107], v[10:13]
	v_mfma_f32_16x16x32_bf16 v[6:9], v[96:99], v[108:111], v[6:9]
	v_mfma_f32_16x16x32_bf16 v[2:5], v[100:103], v[108:111], v[2:5]
	s_add_i32 s21, s21, 8
	s_addk_i32 s24, 0x100
	s_cmp_gt_i32 s21, 55
	s_cbranch_scc1 .Lmy_sq0_done
	v_mfma_f32_16x16x32_bf16 v[14:17], v[48:51], v[56:59], v[14:17]
	v_mfma_f32_16x16x32_bf16 v[10:13], v[52:55], v[56:59], v[10:13]
	v_mfma_f32_16x16x32_bf16 v[6:9], v[48:51], v[60:63], v[6:9]
	v_mfma_f32_16x16x32_bf16 v[2:5], v[52:55], v[60:63], v[2:5]
	s_add_i32 s21, s21, 8
	s_addk_i32 s24, 0x100
	s_cmp_gt_i32 s21, 55
	s_cbranch_scc1 .Lmy_sq0_done
	v_mfma_f32_16x16x32_bf16 v[14:17], v[64:67], v[72:75], v[14:17]
	v_mfma_f32_16x16x32_bf16 v[10:13], v[68:71], v[72:75], v[10:13]
	v_mfma_f32_16x16x32_bf16 v[6:9], v[64:67], v[76:79], v[6:9]
	v_mfma_f32_16x16x32_bf16 v[2:5], v[68:71], v[76:79], v[2:5]
	s_add_i32 s21, s21, 8
	s_addk_i32 s24, 0x100
	s_cmp_gt_i32 s21, 55
	s_cbranch_scc1 .Lmy_sq0_done
	s_branch .Lmy_sq0_done
.Lmy_sq0_tail3:
	s_waitcnt vmcnt(0)
	v_mfma_f32_16x16x32_bf16 v[14:17], v[48:51], v[56:59], v[14:17]
	v_mfma_f32_16x16x32_bf16 v[10:13], v[52:55], v[56:59], v[10:13]
	v_mfma_f32_16x16x32_bf16 v[6:9], v[48:51], v[60:63], v[6:9]
	v_mfma_f32_16x16x32_bf16 v[2:5], v[52:55], v[60:63], v[2:5]
	s_add_i32 s21, s21, 8
	s_addk_i32 s24, 0x100
	s_cmp_gt_i32 s21, 55
	s_cbranch_scc1 .Lmy_sq0_done
	v_mfma_f32_16x16x32_bf16 v[14:17], v[64:67], v[72:75], v[14:17]
	v_mfma_f32_16x16x32_bf16 v[10:13], v[68:71], v[72:75], v[10:13]
	v_mfma_f32_16x16x32_bf16 v[6:9], v[64:67], v[76:79], v[6:9]
	v_mfma_f32_16x16x32_bf16 v[2:5], v[68:71], v[76:79], v[2:5]
	s_add_i32 s21, s21, 8
	s_addk_i32 s24, 0x100
	s_cmp_gt_i32 s21, 55
	s_cbranch_scc1 .Lmy_sq0_done
	v_mfma_f32_16x16x32_bf16 v[14:17], v[80:83], v[88:91], v[14:17]
	v_mfma_f32_16x16x32_bf16 v[10:13], v[84:87], v[88:91], v[10:13]
	v_mfma_f32_16x16x32_bf16 v[6:9], v[80:83], v[92:95], v[6:9]
	v_mfma_f32_16x16x32_bf16 v[2:5], v[84:87], v[92:95], v[2:5]
	s_add_i32 s21, s21, 8
	s_addk_i32 s24, 0x100
	s_cmp_gt_i32 s21, 55
	s_cbranch_scc1 .Lmy_sq0_done
	s_branch .Lmy_sq0_done

.LBB0_722:
	s_add_i32 s100, s18, 0x0
	s_ashr_i32 s101, s100, 31
	s_lshl_b64 s[100:101], s[100:101], 1
	v_lshl_add_u64 v[48:49], v[18:19], 0, s[100:101]
	v_lshl_add_u64 v[52:53], v[22:23], 0, s[100:101]
	v_lshl_add_u64 v[56:57], v[20:21], 0, s[100:101]
	v_lshl_add_u64 v[60:61], v[24:25], 0, s[100:101]
	global_load_dwordx4 v[48:51], v[48:49], off
	global_load_dwordx4 v[52:55], v[52:53], off
	global_load_dwordx4 v[56:59], v[56:57], off
	global_load_dwordx4 v[60:63], v[60:61], off
	s_cmp_gt_i32 s6, 47
	s_cbranch_scc1 .Lmy_sq1_tail3
	s_add_i32 s100, s18, 0x100
	s_ashr_i32 s101, s100, 31
	s_lshl_b64 s[100:101], s[100:101], 1
	v_lshl_add_u64 v[64:65], v[18:19], 0, s[100:101]
	v_lshl_add_u64 v[68:69], v[22:23], 0, s[100:101]
	v_lshl_add_u64 v[72:73], v[20:21], 0, s[100:101]
	v_lshl_add_u64 v[76:77], v[24:25], 0, s[100:101]
	global_load_dwordx4 v[64:67], v[64:65], off
	global_load_dwordx4 v[68:71], v[68:69], off
	global_load_dwordx4 v[72:75], v[72:73], off
	global_load_dwordx4 v[76:79], v[76:77], off
	s_cmp_gt_i32 s6, 39
	s_cbranch_scc1 .Lmy_sq1_tail3
	s_add_i32 s100, s18, 0x200
	s_ashr_i32 s101, s100, 31
	s_lshl_b64 s[100:101], s[100:101], 1
	v_lshl_add_u64 v[80:81], v[18:19], 0, s[100:101]
	v_lshl_add_u64 v[84:85], v[22:23], 0, s[100:101]
	v_lshl_add_u64 v[88:89], v[20:21], 0, s[100:101]
	v_lshl_add_u64 v[92:93], v[24:25], 0, s[100:101]
	global_load_dwordx4 v[80:83], v[80:81], off
	global_load_dwordx4 v[84:87], v[84:85], off
	global_load_dwordx4 v[88:91], v[88:89], off
	global_load_dwordx4 v[92:95], v[92:93], off
	s_cmp_gt_i32 s6, 31
	s_cbranch_scc1 .Lmy_sq1_tail3
	s_add_i32 s100, s18, 0x300
	s_ashr_i32 s101, s100, 31
	s_lshl_b64 s[100:101], s[100:101], 1
	v_lshl_add_u64 v[96:97], v[18:19], 0, s[100:101]
	v_lshl_add_u64 v[100:101], v[22:23], 0, s[100:101]
	v_lshl_add_u64 v[104:105], v[20:21], 0, s[100:101]
	v_lshl_add_u64 v[108:109], v[24:25], 0, s[100:101]
	global_load_dwordx4 v[96:99], v[96:97], off
	global_load_dwordx4 v[100:103], v[100:101], off
	global_load_dwordx4 v[104:107], v[104:105], off
	global_load_dwordx4 v[108:111], v[108:109], off
.Lmy_sq1_loop:
	s_waitcnt vmcnt(12)
	v_mfma_f32_16x16x32_bf16 v[14:17], v[48:51], v[56:59], v[14:17]
	v_mfma_f32_16x16x32_bf16 v[10:13], v[52:55], v[56:59], v[10:13]
	v_mfma_f32_16x16x32_bf16 v[6:9], v[48:51], v[60:63], v[6:9]
	v_mfma_f32_16x16x32_bf16 v[2:5], v[52:55], v[60:63], v[2:5]
	s_add_i32 s6, s6, 8
	s_addk_i32 s18, 0x100
	s_cmp_gt_i32 s6, 55
	s_cbranch_scc1 .Lmy_sq1_done
	s_cmp_gt_i32 s6, 31
	s_cbranch_scc1 .Lmy_sq1_tail0
	s_add_i32 s100, s18, 0x300
	s_ashr_i32 s101, s100, 31
	s_lshl_b64 s[100:101], s[100:101], 1
	v_lshl_add_u64 v[48:49], v[18:19], 0, s[100:101]
	v_lshl_add_u64 v[52:53], v[22:23], 0, s[100:101]
	v_lshl_add_u64 v[56:57], v[20:21], 0, s[100:101]
	v_lshl_add_u64 v[60:61], v[24:25], 0, s[100:101]
	global_load_dwordx4 v[48:51], v[48:49], off
	global_load_dwordx4 v[52:55], v[52:53], off
	global_load_dwordx4 v[56:59], v[56:57], off
	global_load_dwordx4 v[60:63], v[60:61], off
	s_waitcnt vmcnt(12)
	v_mfma_f32_16x16x32_bf16 v[14:17], v[64:67], v[72:75], v[14:17]
	v_mfma_f32_16x16x32_bf16 v[10:13], v[68:71], v[72:75], v[10:13]
	v_mfma_f32_16x16x32_bf16 v[6:9], v[64:67], v[76:79], v[6:9]
	v_mfma_f32_16x16x32_bf16 v[2:5], v[68:71], v[76:79], v[2:5]
	s_add_i32 s6, s6, 8
	s_addk_i32 s18, 0x100
	s_cmp_gt_i32 s6, 55
	s_cbranch_scc1 .Lmy_sq1_done
	s_cmp_gt_i32 s6, 31
	s_cbranch_scc1 .Lmy_sq1_tail1
	s_add_i32 s100, s18, 0x300
	s_ashr_i32 s101, s100, 31
	s_lshl_b64 s[100:101], s[100:101], 1
	v_lshl_add_u64 v[64:65], v[18:19], 0, s[100:101]
	v_lshl_add_u64 v[68:69], v[22:23], 0, s[100:101]
	v_lshl_add_u64 v[72:73], v[20:21], 0, s[100:101]
	v_lshl_add_u64 v[76:77], v[24:25], 0, s[100:101]
	global_load_dwordx4 v[64:67], v[64:65], off
	global_load_dwordx4 v[68:71], v[68:69], off
	global_load_dwordx4 v[72:75], v[72:73], off
	global_load_dwordx4 v[76:79], v[76:77], off
	s_waitcnt vmcnt(12)
	v_mfma_f32_16x16x32_bf16 v[14:17], v[80:83], v[88:91], v[14:17]
	v_mfma_f32_16x16x32_bf16 v[10:13], v[84:87], v[88:91], v[10:13]
	v_mfma_f32_16x16x32_bf16 v[6:9], v[80:83], v[92:95], v[6:9]
	v_mfma_f32_16x16x32_bf16 v[2:5], v[84:87], v[92:95], v[2:5]
	s_add_i32 s6, s6, 8
	s_addk_i32 s18, 0x100
	s_cmp_gt_i32 s6, 55
	s_cbranch_scc1 .Lmy_sq1_done
	s_cmp_gt_i32 s6, 31
	s_cbranch_scc1 .Lmy_sq1_tail2
	s_add_i32 s100, s18, 0x300
	s_ashr_i32 s101, s100, 31
	s_lshl_b64 s[100:101], s[100:101], 1
	v_lshl_add_u64 v[80:81], v[18:19], 0, s[100:101]
	v_lshl_add_u64 v[84:85], v[22:23], 0, s[100:101]
	v_lshl_add_u64 v[88:89], v[20:21], 0, s[100:101]
	v_lshl_add_u64 v[92:93], v[24:25], 0, s[100:101]
	global_load_dwordx4 v[80:83], v[80:81], off
	global_load_dwordx4 v[84:87], v[84:85], off
	global_load_dwordx4 v[88:91], v[88:89], off
	global_load_dwordx4 v[92:95], v[92:93], off
	s_waitcnt vmcnt(12)
	v_mfma_f32_16x16x32_bf16 v[14:17], v[96:99], v[104:107], v[14:17]
	v_mfma_f32_16x16x32_bf16 v[10:13], v[100:103], v[104:107], v[10:13]
	v_mfma_f32_16x16x32_bf16 v[6:9], v[96:99], v[108:111], v[6:9]
	v_mfma_f32_16x16x32_bf16 v[2:5], v[100:103], v[108:111], v[2:5]
	s_add_i32 s6, s6, 8
	s_addk_i32 s18, 0x100
	s_cmp_gt_i32 s6, 55
	s_cbranch_scc1 .Lmy_sq1_done
	s_cmp_gt_i32 s6, 31
	s_cbranch_scc1 .Lmy_sq1_tail3
	s_add_i32 s100, s18, 0x300
	s_ashr_i32 s101, s100, 31
	s_lshl_b64 s[100:101], s[100:101], 1
	v_lshl_add_u64 v[96:97], v[18:19], 0, s[100:101]
	v_lshl_add_u64 v[100:101], v[22:23], 0, s[100:101]
	v_lshl_add_u64 v[104:105], v[20:21], 0, s[100:101]
	v_lshl_add_u64 v[108:109], v[24:25], 0, s[100:101]
	global_load_dwordx4 v[96:99], v[96:97], off
	global_load_dwordx4 v[100:103], v[100:101], off
	global_load_dwordx4 v[104:107], v[104:105], off
	global_load_dwordx4 v[108:111], v[108:109], off
	s_branch .Lmy_sq1_loop
.Lmy_sq1_tail0:
	s_waitcnt vmcnt(0)
	v_mfma_f32_16x16x32_bf16 v[14:17], v[64:67], v[72:75], v[14:17]
	v_mfma_f32_16x16x32_bf16 v[10:13], v[68:71], v[72:75], v[10:13]
	v_mfma_f32_16x16x32_bf16 v[6:9], v[64:67], v[76:79], v[6:9]
	v_mfma_f32_16x16x32_bf16 v[2:5], v[68:71], v[76:79], v[2:5]
	s_add_i32 s6, s6, 8
	s_addk_i32 s18, 0x100
	s_cmp_gt_i32 s6, 55
	s_cbranch_scc1 .Lmy_sq1_done
	v_mfma_f32_16x16x32_bf16 v[14:17], v[80:83], v[88:91], v[14:17]
	v_mfma_f32_16x16x32_bf16 v[10:13], v[84:87], v[88:91], v[10:13]
	v_mfma_f32_16x16x32_bf16 v[6:9], v[80:83], v[92:95], v[6:9]
	v_mfma_f32_16x16x32_bf16 v[2:5], v[84:87], v[92:95], v[2:5]
	s_add_i32 s6, s6, 8
	s_addk_i32 s18, 0x100
	s_cmp_gt_i32 s6, 55
	s_cbranch_scc1 .Lmy_sq1_done
	v_mfma_f32_16x16x32_bf16 v[14:17], v[96:99], v[104:107], v[14:17]
	v_mfma_f32_16x16x32_bf16 v[10:13], v[100:103], v[104:107], v[10:13]
	v_mfma_f32_16x16x32_bf16 v[6:9], v[96:99], v[108:111], v[6:9]
	v_mfma_f32_16x16x32_bf16 v[2:5], v[100:103], v[108:111], v[2:5]
	s_add_i32 s6, s6, 8
	s_addk_i32 s18, 0x100
	s_cmp_gt_i32 s6, 55
	s_cbranch_scc1 .Lmy_sq1_done
	s_branch .Lmy_sq1_done
.Lmy_sq1_tail1:
	s_waitcnt vmcnt(0)
	v_mfma_f32_16x16x32_bf16 v[14:17], v[80:83], v[88:91], v[14:17]
	v_mfma_f32_16x16x32_bf16 v[10:13], v[84:87], v[88:91], v[10:13]
	v_mfma_f32_16x16x32_bf16 v[6:9], v[80:83], v[92:95], v[6:9]
	v_mfma_f32_16x16x32_bf16 v[2:5], v[84:87], v[92:95], v[2:5]
	s_add_i32 s6, s6, 8
	s_addk_i32 s18, 0x100
	s_cmp_gt_i32 s6, 55
	s_cbranch_scc1 .Lmy_sq1_done
	v_mfma_f32_16x16x32_bf16 v[14:17], v[96:99], v[104:107], v[14:17]
	v_mfma_f32_16x16x32_bf16 v[10:13], v[100:103], v[104:107], v[10:13]
	v_mfma_f32_16x16x32_bf16 v[6:9], v[96:99], v[108:111], v[6:9]
	v_mfma_f32_16x16x32_bf16 v[2:5], v[100:103], v[108:111], v[2:5]
	s_add_i32 s6, s6, 8
	s_addk_i32 s18, 0x100
	s_cmp_gt_i32 s6, 55
	s_cbranch_scc1 .Lmy_sq1_done
	v_mfma_f32_16x16x32_bf16 v[14:17], v[48:51], v[56:59], v[14:17]
	v_mfma_f32_16x16x32_bf16 v[10:13], v[52:55], v[56:59], v[10:13]
	v_mfma_f32_16x16x32_bf16 v[6:9], v[48:51], v[60:63], v[6:9]
	v_mfma_f32_16x16x32_bf16 v[2:5], v[52:55], v[60:63], v[2:5]
	s_add_i32 s6, s6, 8
	s_addk_i32 s18, 0x100
	s_cmp_gt_i32 s6, 55
	s_cbranch_scc1 .Lmy_sq1_done
	s_branch .Lmy_sq1_done
.Lmy_sq1_tail2:
	s_waitcnt vmcnt(0)
	v_mfma_f32_16x16x32_bf16 v[14:17], v[96:99], v[104:107], v[14:17]
	v_mfma_f32_16x16x32_bf16 v[10:13], v[100:103], v[104:107], v[10:13]
	v_mfma_f32_16x16x32_bf16 v[6:9], v[96:99], v[108:111], v[6:9]
	v_mfma_f32_16x16x32_bf16 v[2:5], v[100:103], v[108:111], v[2:5]
	s_add_i32 s6, s6, 8
	s_addk_i32 s18, 0x100
	s_cmp_gt_i32 s6, 55
	s_cbranch_scc1 .Lmy_sq1_done
	v_mfma_f32_16x16x32_bf16 v[14:17], v[48:51], v[56:59], v[14:17]
	v_mfma_f32_16x16x32_bf16 v[10:13], v[52:55], v[56:59], v[10:13]
	v_mfma_f32_16x16x32_bf16 v[6:9], v[48:51], v[60:63], v[6:9]
	v_mfma_f32_16x16x32_bf16 v[2:5], v[52:55], v[60:63], v[2:5]
	s_add_i32 s6, s6, 8
	s_addk_i32 s18, 0x100
	s_cmp_gt_i32 s6, 55
	s_cbranch_scc1 .Lmy_sq1_done
	v_mfma_f32_16x16x32_bf16 v[14:17], v[64:67], v[72:75], v[14:17]
	v_mfma_f32_16x16x32_bf16 v[10:13], v[68:71], v[72:75], v[10:13]
	v_mfma_f32_16x16x32_bf16 v[6:9], v[64:67], v[76:79], v[6:9]
	v_mfma_f32_16x16x32_bf16 v[2:5], v[68:71], v[76:79], v[2:5]
	s_add_i32 s6, s6, 8
	s_addk_i32 s18, 0x100
	s_cmp_gt_i32 s6, 55
	s_cbranch_scc1 .Lmy_sq1_done
	s_branch .Lmy_sq1_done
.Lmy_sq1_tail3:
	s_waitcnt vmcnt(0)
	v_mfma_f32_16x16x32_bf16 v[14:17], v[48:51], v[56:59], v[14:17]
	v_mfma_f32_16x16x32_bf16 v[10:13], v[52:55], v[56:59], v[10:13]
	v_mfma_f32_16x16x32_bf16 v[6:9], v[48:51], v[60:63], v[6:9]
	v_mfma_f32_16x16x32_bf16 v[2:5], v[52:55], v[60:63], v[2:5]
	s_add_i32 s6, s6, 8
	s_addk_i32 s18, 0x100
	s_cmp_gt_i32 s6, 55
	s_cbranch_scc1 .Lmy_sq1_done
	v_mfma_f32_16x16x32_bf16 v[14:17], v[64:67], v[72:75], v[14:17]
	v_mfma_f32_16x16x32_bf16 v[10:13], v[68:71], v[72:75], v[10:13]
	v_mfma_f32_16x16x32_bf16 v[6:9], v[64:67], v[76:79], v[6:9]
	v_mfma_f32_16x16x32_bf16 v[2:5], v[68:71], v[76:79], v[2:5]
	s_add_i32 s6, s6, 8
	s_addk_i32 s18, 0x100
	s_cmp_gt_i32 s6, 55
	s_cbranch_scc1 .Lmy_sq1_done
	v_mfma_f32_16x16x32_bf16 v[14:17], v[80:83], v[88:91], v[14:17]
	v_mfma_f32_16x16x32_bf16 v[10:13], v[84:87], v[88:91], v[10:13]
	v_mfma_f32_16x16x32_bf16 v[6:9], v[80:83], v[92:95], v[6:9]
	v_mfma_f32_16x16x32_bf16 v[2:5], v[84:87], v[92:95], v[2:5]
	s_add_i32 s6, s6, 8
	s_addk_i32 s18, 0x100
	s_cmp_gt_i32 s6, 55
	s_cbranch_scc1 .Lmy_sq1_done
	s_branch .Lmy_sq1_done

.LBB0_1878:
	s_add_i32 s100, s22, 0x0
	s_ashr_i32 s101, s100, 31
	s_lshl_b64 s[100:101], s[100:101], 1
	v_lshl_add_u64 v[48:49], v[20:21], 0, s[100:101]
	v_lshl_add_u64 v[52:53], v[24:25], 0, s[100:101]
	v_lshl_add_u64 v[56:57], v[22:23], 0, s[100:101]
	v_lshl_add_u64 v[60:61], v[26:27], 0, s[100:101]
	global_load_dwordx4 v[48:51], v[48:49], off
	global_load_dwordx4 v[52:55], v[52:53], off
	global_load_dwordx4 v[56:59], v[56:57], off
	global_load_dwordx4 v[60:63], v[60:61], off
	s_cmp_gt_i32 s9, 155
	s_cbranch_scc1 .Lmy_sq4_tail3
	s_add_i32 s100, s22, 0x100
	s_ashr_i32 s101, s100, 31
	s_lshl_b64 s[100:101], s[100:101], 1
	v_lshl_add_u64 v[64:65], v[20:21], 0, s[100:101]
	v_lshl_add_u64 v[68:69], v[24:25], 0, s[100:101]
	v_lshl_add_u64 v[72:73], v[22:23], 0, s[100:101]
	v_lshl_add_u64 v[76:77], v[26:27], 0, s[100:101]
	global_load_dwordx4 v[64:67], v[64:65], off
	global_load_dwordx4 v[68:71], v[68:69], off
	global_load_dwordx4 v[72:75], v[72:73], off
	global_load_dwordx4 v[76:79], v[76:77], off
	s_cmp_gt_i32 s9, 147
	s_cbranch_scc1 .Lmy_sq4_tail3
	s_add_i32 s100, s22, 0x200
	s_ashr_i32 s101, s100, 31
	s_lshl_b64 s[100:101], s[100:101], 1
	v_lshl_add_u64 v[80:81], v[20:21], 0, s[100:101]
	v_lshl_add_u64 v[84:85], v[24:25], 0, s[100:101]
	v_lshl_add_u64 v[88:89], v[22:23], 0, s[100:101]
	v_lshl_add_u64 v[92:93], v[26:27], 0, s[100:101]
	global_load_dwordx4 v[80:83], v[80:81], off
	global_load_dwordx4 v[84:87], v[84:85], off
	global_load_dwordx4 v[88:91], v[88:89], off
	global_load_dwordx4 v[92:95], v[92:93], off
	s_cmp_gt_i32 s9, 139
	s_cbranch_scc1 .Lmy_sq4_tail3
	s_add_i32 s100, s22, 0x300
	s_ashr_i32 s101, s100, 31
	s_lshl_b64 s[100:101], s[100:101], 1
	v_lshl_add_u64 v[96:97], v[20:21], 0, s[100:101]
	v_lshl_add_u64 v[100:101], v[24:25], 0, s[100:101]
	v_lshl_add_u64 v[104:105], v[22:23], 0, s[100:101]
	v_lshl_add_u64 v[108:109], v[26:27], 0, s[100:101]
	global_load_dwordx4 v[96:99], v[96:97], off
	global_load_dwordx4 v[100:103], v[100:101], off
	global_load_dwordx4 v[104:107], v[104:105], off
	global_load_dwordx4 v[108:111], v[108:109], off
.Lmy_sq4_loop:
	s_waitcnt vmcnt(12)
	v_mfma_f32_16x16x32_bf16 v[14:17], v[48:51], v[56:59], v[14:17]
	v_mfma_f32_16x16x32_bf16 v[10:13], v[52:55], v[56:59], v[10:13]
	v_mfma_f32_16x16x32_bf16 v[6:9], v[48:51], v[60:63], v[6:9]
	v_mfma_f32_16x16x32_bf16 v[2:5], v[52:55], v[60:63], v[2:5]
	s_add_i32 s9, s9, 8
	s_addk_i32 s22, 0x100
	s_cmp_gt_i32 s9, 163
	s_cbranch_scc1 .Lmy_sq4_done
	s_cmp_gt_i32 s9, 139
	s_cbranch_scc1 .Lmy_sq4_tail0
	s_add_i32 s100, s22, 0x300
	s_ashr_i32 s101, s100, 31
	s_lshl_b64 s[100:101], s[100:101], 1
	v_lshl_add_u64 v[48:49], v[20:21], 0, s[100:101]
	v_lshl_add_u64 v[52:53], v[24:25], 0, s[100:101]
	v_lshl_add_u64 v[56:57], v[22:23], 0, s[100:101]
	v_lshl_add_u64 v[60:61], v[26:27], 0, s[100:101]
	global_load_dwordx4 v[48:51], v[48:49], off
	global_load_dwordx4 v[52:55], v[52:53], off
	global_load_dwordx4 v[56:59], v[56:57], off
	global_load_dwordx4 v[60:63], v[60:61], off
	s_waitcnt vmcnt(12)
	v_mfma_f32_16x16x32_bf16 v[14:17], v[64:67], v[72:75], v[14:17]
	v_mfma_f32_16x16x32_bf16 v[10:13], v[68:71], v[72:75], v[10:13]
	v_mfma_f32_16x16x32_bf16 v[6:9], v[64:67], v[76:79], v[6:9]
	v_mfma_f32_16x16x32_bf16 v[2:5], v[68:71], v[76:79], v[2:5]
	s_add_i32 s9, s9, 8
	s_addk_i32 s22, 0x100
	s_cmp_gt_i32 s9, 163
	s_cbranch_scc1 .Lmy_sq4_done
	s_cmp_gt_i32 s9, 139
	s_cbranch_scc1 .Lmy_sq4_tail1
	s_add_i32 s100, s22, 0x300
	s_ashr_i32 s101, s100, 31
	s_lshl_b64 s[100:101], s[100:101], 1
	v_lshl_add_u64 v[64:65], v[20:21], 0, s[100:101]
	v_lshl_add_u64 v[68:69], v[24:25], 0, s[100:101]
	v_lshl_add_u64 v[72:73], v[22:23], 0, s[100:101]
	v_lshl_add_u64 v[76:77], v[26:27], 0, s[100:101]
	global_load_dwordx4 v[64:67], v[64:65], off
	global_load_dwordx4 v[68:71], v[68:69], off
	global_load_dwordx4 v[72:75], v[72:73], off
	global_load_dwordx4 v[76:79], v[76:77], off
	s_waitcnt vmcnt(12)
	v_mfma_f32_16x16x32_bf16 v[14:17], v[80:83], v[88:91], v[14:17]
	v_mfma_f32_16x16x32_bf16 v[10:13], v[84:87], v[88:91], v[10:13]
	v_mfma_f32_16x16x32_bf16 v[6:9], v[80:83], v[92:95], v[6:9]
	v_mfma_f32_16x16x32_bf16 v[2:5], v[84:87], v[92:95], v[2:5]
	s_add_i32 s9, s9, 8
	s_addk_i32 s22, 0x100
	s_cmp_gt_i32 s9, 163
	s_cbranch_scc1 .Lmy_sq4_done
	s_cmp_gt_i32 s9, 139
	s_cbranch_scc1 .Lmy_sq4_tail2
	s_add_i32 s100, s22, 0x300
	s_ashr_i32 s101, s100, 31
	s_lshl_b64 s[100:101], s[100:101], 1
	v_lshl_add_u64 v[80:81], v[20:21], 0, s[100:101]
	v_lshl_add_u64 v[84:85], v[24:25], 0, s[100:101]
	v_lshl_add_u64 v[88:89], v[22:23], 0, s[100:101]
	v_lshl_add_u64 v[92:93], v[26:27], 0, s[100:101]
	global_load_dwordx4 v[80:83], v[80:81], off
	global_load_dwordx4 v[84:87], v[84:85], off
	global_load_dwordx4 v[88:91], v[88:89], off
	global_load_dwordx4 v[92:95], v[92:93], off
	s_waitcnt vmcnt(12)
	v_mfma_f32_16x16x32_bf16 v[14:17], v[96:99], v[104:107], v[14:17]
	v_mfma_f32_16x16x32_bf16 v[10:13], v[100:103], v[104:107], v[10:13]
	v_mfma_f32_16x16x32_bf16 v[6:9], v[96:99], v[108:111], v[6:9]
	v_mfma_f32_16x16x32_bf16 v[2:5], v[100:103], v[108:111], v[2:5]
	s_add_i32 s9, s9, 8
	s_addk_i32 s22, 0x100
	s_cmp_gt_i32 s9, 163
	s_cbranch_scc1 .Lmy_sq4_done
	s_cmp_gt_i32 s9, 139
	s_cbranch_scc1 .Lmy_sq4_tail3
	s_add_i32 s100, s22, 0x300
	s_ashr_i32 s101, s100, 31
	s_lshl_b64 s[100:101], s[100:101], 1
	v_lshl_add_u64 v[96:97], v[20:21], 0, s[100:101]
	v_lshl_add_u64 v[100:101], v[24:25], 0, s[100:101]
	v_lshl_add_u64 v[104:105], v[22:23], 0, s[100:101]
	v_lshl_add_u64 v[108:109], v[26:27], 0, s[100:101]
	global_load_dwordx4 v[96:99], v[96:97], off
	global_load_dwordx4 v[100:103], v[100:101], off
	global_load_dwordx4 v[104:107], v[104:105], off
	global_load_dwordx4 v[108:111], v[108:109], off
	s_branch .Lmy_sq4_loop
.Lmy_sq4_tail0:
	s_waitcnt vmcnt(0)
	v_mfma_f32_16x16x32_bf16 v[14:17], v[64:67], v[72:75], v[14:17]
	v_mfma_f32_16x16x32_bf16 v[10:13], v[68:71], v[72:75], v[10:13]
	v_mfma_f32_16x16x32_bf16 v[6:9], v[64:67], v[76:79], v[6:9]
	v_mfma_f32_16x16x32_bf16 v[2:5], v[68:71], v[76:79], v[2:5]
	s_add_i32 s9, s9, 8
	s_addk_i32 s22, 0x100
	s_cmp_gt_i32 s9, 163
	s_cbranch_scc1 .Lmy_sq4_done
	v_mfma_f32_16x16x32_bf16 v[14:17], v[80:83], v[88:91], v[14:17]
	v_mfma_f32_16x16x32_bf16 v[10:13], v[84:87], v[88:91], v[10:13]
	v_mfma_f32_16x16x32_bf16 v[6:9], v[80:83], v[92:95], v[6:9]
	v_mfma_f32_16x16x32_bf16 v[2:5], v[84:87], v[92:95], v[2:5]
	s_add_i32 s9, s9, 8
	s_addk_i32 s22, 0x100
	s_cmp_gt_i32 s9, 163
	s_cbranch_scc1 .Lmy_sq4_done
	v_mfma_f32_16x16x32_bf16 v[14:17], v[96:99], v[104:107], v[14:17]
	v_mfma_f32_16x16x32_bf16 v[10:13], v[100:103], v[104:107], v[10:13]
	v_mfma_f32_16x16x32_bf16 v[6:9], v[96:99], v[108:111], v[6:9]
	v_mfma_f32_16x16x32_bf16 v[2:5], v[100:103], v[108:111], v[2:5]
	s_add_i32 s9, s9, 8
	s_addk_i32 s22, 0x100
	s_cmp_gt_i32 s9, 163
	s_cbranch_scc1 .Lmy_sq4_done
	s_branch .Lmy_sq4_done
.Lmy_sq4_tail1:
	s_waitcnt vmcnt(0)
	v_mfma_f32_16x16x32_bf16 v[14:17], v[80:83], v[88:91], v[14:17]
	v_mfma_f32_16x16x32_bf16 v[10:13], v[84:87], v[88:91], v[10:13]
	v_mfma_f32_16x16x32_bf16 v[6:9], v[80:83], v[92:95], v[6:9]
	v_mfma_f32_16x16x32_bf16 v[2:5], v[84:87], v[92:95], v[2:5]
	s_add_i32 s9, s9, 8
	s_addk_i32 s22, 0x100
	s_cmp_gt_i32 s9, 163
	s_cbranch_scc1 .Lmy_sq4_done
	v_mfma_f32_16x16x32_bf16 v[14:17], v[96:99], v[104:107], v[14:17]
	v_mfma_f32_16x16x32_bf16 v[10:13], v[100:103], v[104:107], v[10:13]
	v_mfma_f32_16x16x32_bf16 v[6:9], v[96:99], v[108:111], v[6:9]
	v_mfma_f32_16x16x32_bf16 v[2:5], v[100:103], v[108:111], v[2:5]
	s_add_i32 s9, s9, 8
	s_addk_i32 s22, 0x100
	s_cmp_gt_i32 s9, 163
	s_cbranch_scc1 .Lmy_sq4_done
	v_mfma_f32_16x16x32_bf16 v[14:17], v[48:51], v[56:59], v[14:17]
	v_mfma_f32_16x16x32_bf16 v[10:13], v[52:55], v[56:59], v[10:13]
	v_mfma_f32_16x16x32_bf16 v[6:9], v[48:51], v[60:63], v[6:9]
	v_mfma_f32_16x16x32_bf16 v[2:5], v[52:55], v[60:63], v[2:5]
	s_add_i32 s9, s9, 8
	s_addk_i32 s22, 0x100
	s_cmp_gt_i32 s9, 163
	s_cbranch_scc1 .Lmy_sq4_done
	s_branch .Lmy_sq4_done
.Lmy_sq4_tail2:
	s_waitcnt vmcnt(0)
	v_mfma_f32_16x16x32_bf16 v[14:17], v[96:99], v[104:107], v[14:17]
	v_mfma_f32_16x16x32_bf16 v[10:13], v[100:103], v[104:107], v[10:13]
	v_mfma_f32_16x16x32_bf16 v[6:9], v[96:99], v[108:111], v[6:9]
	v_mfma_f32_16x16x32_bf16 v[2:5], v[100:103], v[108:111], v[2:5]
	s_add_i32 s9, s9, 8
	s_addk_i32 s22, 0x100
	s_cmp_gt_i32 s9, 163
	s_cbranch_scc1 .Lmy_sq4_done
	v_mfma_f32_16x16x32_bf16 v[14:17], v[48:51], v[56:59], v[14:17]
	v_mfma_f32_16x16x32_bf16 v[10:13], v[52:55], v[56:59], v[10:13]
	v_mfma_f32_16x16x32_bf16 v[6:9], v[48:51], v[60:63], v[6:9]
	v_mfma_f32_16x16x32_bf16 v[2:5], v[52:55], v[60:63], v[2:5]
	s_add_i32 s9, s9, 8
	s_addk_i32 s22, 0x100
	s_cmp_gt_i32 s9, 163
	s_cbranch_scc1 .Lmy_sq4_done
	v_mfma_f32_16x16x32_bf16 v[14:17], v[64:67], v[72:75], v[14:17]
	v_mfma_f32_16x16x32_bf16 v[10:13], v[68:71], v[72:75], v[10:13]
	v_mfma_f32_16x16x32_bf16 v[6:9], v[64:67], v[76:79], v[6:9]
	v_mfma_f32_16x16x32_bf16 v[2:5], v[68:71], v[76:79], v[2:5]
	s_add_i32 s9, s9, 8
	s_addk_i32 s22, 0x100
	s_cmp_gt_i32 s9, 163
	s_cbranch_scc1 .Lmy_sq4_done
	s_branch .Lmy_sq4_done
.Lmy_sq4_tail3:
	s_waitcnt vmcnt(0)
	v_mfma_f32_16x16x32_bf16 v[14:17], v[48:51], v[56:59], v[14:17]
	v_mfma_f32_16x16x32_bf16 v[10:13], v[52:55], v[56:59], v[10:13]
	v_mfma_f32_16x16x32_bf16 v[6:9], v[48:51], v[60:63], v[6:9]
	v_mfma_f32_16x16x32_bf16 v[2:5], v[52:55], v[60:63], v[2:5]
	s_add_i32 s9, s9, 8
	s_addk_i32 s22, 0x100
	s_cmp_gt_i32 s9, 163
	s_cbranch_scc1 .Lmy_sq4_done
	v_mfma_f32_16x16x32_bf16 v[14:17], v[64:67], v[72:75], v[14:17]
	v_mfma_f32_16x16x32_bf16 v[10:13], v[68:71], v[72:75], v[10:13]
	v_mfma_f32_16x16x32_bf16 v[6:9], v[64:67], v[76:79], v[6:9]
	v_mfma_f32_16x16x32_bf16 v[2:5], v[68:71], v[76:79], v[2:5]
	s_add_i32 s9, s9, 8
	s_addk_i32 s22, 0x100
	s_cmp_gt_i32 s9, 163
	s_cbranch_scc1 .Lmy_sq4_done
	v_mfma_f32_16x16x32_bf16 v[14:17], v[80:83], v[88:91], v[14:17]
	v_mfma_f32_16x16x32_bf16 v[10:13], v[84:87], v[88:91], v[10:13]
	v_mfma_f32_16x16x32_bf16 v[6:9], v[80:83], v[92:95], v[6:9]
	v_mfma_f32_16x16x32_bf16 v[2:5], v[84:87], v[92:95], v[2:5]
	s_add_i32 s9, s9, 8
	s_addk_i32 s22, 0x100
	s_cmp_gt_i32 s9, 163
	s_cbranch_scc1 .Lmy_sq4_done
	s_branch .Lmy_sq4_done
